# win epilogue store part rewritten: 8 LDS reads in flight, incremental 64-bit store addresses instead of per-store 64-bit multiplies
# speedup vs baseline: 1.0039x; 1.0016x over previous
; template <int MI, int NJ> ...
;     ...
;   for (int kt = 0; kt < nk; ++kt) {
;     const int buf = kt & 1;
;     {
;       G8STORE(buf ^ 1);
;       const u16* ga_ = (kt + 2 < nk) ? Ag + (kt + 2) * 64 : Ag + nAoff;
;       const u16* gb_ = (kt + 2 < nk) ? Bg + (kt + 2) * 64 : Bg + nBoff;
;       G8LOADP(ga_, gb_);
;     }
;     __builtin_amdgcn_sched_barrier(0);
;     __builtin_amdgcn_s_setprio(1);
;     const u16* a = ra_ + buf * AROWS * 64;
;     const u16* b = rb_ + buf * BROWS * 64;
; #pragma unroll
;     for (int ks = 0; ks < 2; ++ks) {
;       const u16* a_ = ks ? a + dsw : a;
;       const u16* b_ = ks ? b + dsw : b;
;       bf16x8 bfr[NJ];
; #pragma unroll
;       for (int j = 0; j < NJ; ++j) bfr[j] = *(const bf16x8*)(b_ + j * 16 * 64);
; #pragma unroll
;       for (int ih = 0; ih < MI / 4; ++ih) {
;         bf16x8 af[4];
; #pragma unroll
;         for (int i = 0; i < 4; ++i) af[i] = *(const bf16x8*)(a_ + (ih * 4 + i) * 16 * 64);
; #pragma unroll
;         for (int i = 0; i < 4; ++i)
; #pragma unroll
;           for (int j = 0; j < NJ; ++j) acc[ih * 4 + i][j] = mfma16(af[i], bfr[j], acc[ih * 4 + i][j]);
;       }
;     }
;     __builtin_amdgcn_s_setprio(0);
;     __builtin_amdgcn_sched_barrier(0);
;     __syncthreads();
;   }
.LBB0_470:
	s_setprio 1
	s_waitcnt lgkmcnt(6)
	v_mfma_f32_16x16x32_bf16 v[158:161], v[166:169], v[162:165], v[158:161]
	s_waitcnt lgkmcnt(5)
	v_mfma_f32_16x16x32_bf16 v[154:157], v[170:173], v[162:165], v[154:157]
	s_waitcnt lgkmcnt(4)
	v_mfma_f32_16x16x32_bf16 v[150:153], v[192:195], v[162:165], v[150:153]
	s_waitcnt lgkmcnt(3)
	v_mfma_f32_16x16x32_bf16 v[146:149], v[196:199], v[162:165], v[146:149]
	ds_read_b128 v[162:165], v0 offset:8192
	s_waitcnt lgkmcnt(3)
	v_mfma_f32_16x16x32_bf16 v[142:145], v[166:169], v[204:207], v[142:145]
	v_mfma_f32_16x16x32_bf16 v[138:141], v[170:173], v[204:207], v[138:141]
	v_mfma_f32_16x16x32_bf16 v[134:137], v[192:195], v[204:207], v[134:137]
	v_mfma_f32_16x16x32_bf16 v[130:133], v[196:199], v[204:207], v[130:133]
	ds_read_b128 v[204:207], v0 offset:10240
	s_waitcnt lgkmcnt(3)
	v_mfma_f32_16x16x32_bf16 v[126:129], v[166:169], v[208:211], v[126:129]
	v_mfma_f32_16x16x32_bf16 v[122:125], v[170:173], v[208:211], v[122:125]
	v_mfma_f32_16x16x32_bf16 v[118:121], v[192:195], v[208:211], v[118:121]
	v_mfma_f32_16x16x32_bf16 v[114:117], v[196:199], v[208:211], v[114:117]
	ds_read_b128 v[208:211], v0 offset:12288
	ds_read_b128 v[212:215], v191
	ds_read_b128 v[216:219], v191 offset:2048
	s_waitcnt lgkmcnt(5)
	v_mfma_f32_16x16x32_bf16 v[110:113], v[166:169], v[238:241], v[110:113]
	v_mfma_f32_16x16x32_bf16 v[106:109], v[170:173], v[238:241], v[106:109]
	v_mfma_f32_16x16x32_bf16 v[102:105], v[192:195], v[238:241], v[102:105]
	v_mfma_f32_16x16x32_bf16 v[98:101], v[196:199], v[238:241], v[98:101]
	ds_read_b128 v[238:241], v0 offset:14336
	ds_read_b128 v[220:223], v191 offset:4096
	ds_read_b128 v[224:227], v191 offset:6144
	s_waitcnt lgkmcnt(7)
	v_mfma_f32_16x16x32_bf16 v[94:97], v[166:169], v[162:165], v[94:97]
	v_mfma_f32_16x16x32_bf16 v[90:93], v[170:173], v[162:165], v[90:93]
	v_mfma_f32_16x16x32_bf16 v[86:89], v[192:195], v[162:165], v[86:89]
	v_mfma_f32_16x16x32_bf16 v[82:85], v[196:199], v[162:165], v[82:85]
	v_add_u32_e32 v0, v0, v190
	ds_read_b128 v[162:165], v0
	s_waitcnt vmcnt(7)
	ds_write_b128 v228, v[10:13]
	global_load_dwordx4 v[10:13], v234, s[52:53]
	s_waitcnt lgkmcnt(8)
	v_mfma_f32_16x16x32_bf16 v[78:81], v[166:169], v[204:207], v[78:81]
	v_mfma_f32_16x16x32_bf16 v[74:77], v[170:173], v[204:207], v[74:77]
	v_mfma_f32_16x16x32_bf16 v[70:73], v[192:195], v[204:207], v[70:73]
	v_mfma_f32_16x16x32_bf16 v[66:69], v[196:199], v[204:207], v[66:69]
	ds_read_b128 v[204:207], v0 offset:2048
	s_waitcnt vmcnt(7)
	ds_write_b128 v228, v[2:5] offset:8192
	global_load_dwordx4 v[2:5], v235, s[52:53]
	s_waitcnt lgkmcnt(9)
	v_mfma_f32_16x16x32_bf16 v[62:65], v[166:169], v[208:211], v[62:65]
	v_mfma_f32_16x16x32_bf16 v[58:61], v[170:173], v[208:211], v[58:61]
	v_mfma_f32_16x16x32_bf16 v[54:57], v[192:195], v[208:211], v[54:57]
	v_mfma_f32_16x16x32_bf16 v[50:53], v[196:199], v[208:211], v[50:53]
	ds_read_b128 v[208:211], v0 offset:4096
	s_waitcnt vmcnt(7)
	ds_write_b128 v228, v[6:9] offset:16384
	global_load_dwordx4 v[6:9], v236, s[52:53]
	s_waitcnt lgkmcnt(8)
	v_mfma_f32_16x16x32_bf16 v[46:49], v[166:169], v[238:241], v[46:49]
	v_mfma_f32_16x16x32_bf16 v[42:45], v[170:173], v[238:241], v[42:45]
	v_mfma_f32_16x16x32_bf16 v[38:41], v[192:195], v[238:241], v[38:41]
	v_mfma_f32_16x16x32_bf16 v[34:37], v[196:199], v[238:241], v[34:37]
	ds_read_b128 v[238:241], v0 offset:6144
	s_waitcnt vmcnt(7)
	ds_write_b128 v228, v[18:21] offset:24576
	global_load_dwordx4 v[18:21], v237, s[52:53]
	s_waitcnt lgkmcnt(7)
	v_mfma_f32_16x16x32_bf16 v[158:161], v[212:215], v[162:165], v[158:161]
	v_mfma_f32_16x16x32_bf16 v[154:157], v[216:219], v[162:165], v[154:157]
	v_mfma_f32_16x16x32_bf16 v[150:153], v[220:223], v[162:165], v[150:153]
	v_mfma_f32_16x16x32_bf16 v[146:149], v[224:227], v[162:165], v[146:149]
	ds_read_b128 v[162:165], v0 offset:8192
	s_waitcnt vmcnt(7)
	ds_write_b128 v229, v[14:17]
	global_load_dwordx4 v[14:17], v234, s[66:67]
	s_waitcnt lgkmcnt(7)
	v_mfma_f32_16x16x32_bf16 v[142:145], v[212:215], v[204:207], v[142:145]
	v_mfma_f32_16x16x32_bf16 v[138:141], v[216:219], v[204:207], v[138:141]
	v_mfma_f32_16x16x32_bf16 v[134:137], v[220:223], v[204:207], v[134:137]
	v_mfma_f32_16x16x32_bf16 v[130:133], v[224:227], v[204:207], v[130:133]
	ds_read_b128 v[204:207], v0 offset:10240
	s_waitcnt vmcnt(7)
	ds_write_b128 v229, v[22:25] offset:8192
	global_load_dwordx4 v[22:25], v235, s[66:67]
	s_waitcnt lgkmcnt(7)
	v_mfma_f32_16x16x32_bf16 v[126:129], v[212:215], v[208:211], v[126:129]
	v_mfma_f32_16x16x32_bf16 v[122:125], v[216:219], v[208:211], v[122:125]
	v_mfma_f32_16x16x32_bf16 v[118:121], v[220:223], v[208:211], v[118:121]
	v_mfma_f32_16x16x32_bf16 v[114:117], v[224:227], v[208:211], v[114:117]
	ds_read_b128 v[208:211], v0 offset:12288
	s_waitcnt vmcnt(7)
	ds_write_b128 v229, v[26:29] offset:16384
	global_load_dwordx4 v[26:29], v236, s[66:67]
	s_waitcnt lgkmcnt(7)
	v_mfma_f32_16x16x32_bf16 v[110:113], v[212:215], v[238:241], v[110:113]
	v_mfma_f32_16x16x32_bf16 v[106:109], v[216:219], v[238:241], v[106:109]
	v_mfma_f32_16x16x32_bf16 v[102:105], v[220:223], v[238:241], v[102:105]
	v_mfma_f32_16x16x32_bf16 v[98:101], v[224:227], v[238:241], v[98:101]
	ds_read_b128 v[238:241], v0 offset:14336
	s_waitcnt vmcnt(7)
	ds_write_b128 v229, v[30:33] offset:24576
	global_load_dwordx4 v[30:33], v237, s[66:67]
	s_waitcnt lgkmcnt(7)
	v_mfma_f32_16x16x32_bf16 v[94:97], v[212:215], v[162:165], v[94:97]
	v_mfma_f32_16x16x32_bf16 v[90:93], v[216:219], v[162:165], v[90:93]
	v_mfma_f32_16x16x32_bf16 v[86:89], v[220:223], v[162:165], v[86:89]
	v_mfma_f32_16x16x32_bf16 v[82:85], v[224:227], v[162:165], v[82:85]
	s_waitcnt lgkmcnt(0)
	s_setprio 0
	s_barrier
; template <int MI, int NJ> ...
;     ...
;   for (int kt = 0; kt < nk; ++kt) {
;     const int buf = kt & 1;
;     {
;       G8STORE(buf ^ 1);
;       const u16* ga_ = (kt + 2 < nk) ? Ag + (kt + 2) * 64 : Ag + nAoff;
;       const u16* gb_ = (kt + 2 < nk) ? Bg + (kt + 2) * 64 : Bg + nBoff;
;       G8LOADP(ga_, gb_);
;     }
;     __builtin_amdgcn_sched_barrier(0);
;     __builtin_amdgcn_s_setprio(1);
;     const u16* a = ra_ + buf * AROWS * 64;
;     const u16* b = rb_ + buf * BROWS * 64;
; #pragma unroll
;     for (int ks = 0; ks < 2; ++ks) {
;       const u16* a_ = ks ? a + dsw : a;
;       const u16* b_ = ks ? b + dsw : b;
;       bf16x8 bfr[NJ];
; #pragma unroll
;       for (int j = 0; j < NJ; ++j) bfr[j] = *(const bf16x8*)(b_ + j * 16 * 64);
; #pragma unroll
;       for (int ih = 0; ih < MI / 4; ++ih) {
;         bf16x8 af[4];
; #pragma unroll
;         for (int i = 0; i < 4; ++i) af[i] = *(const bf16x8*)(a_ + (ih * 4 + i) * 16 * 64);
; #pragma unroll
;         for (int i = 0; i < 4; ++i)
; #pragma unroll
;           for (int j = 0; j < NJ; ++j) acc[ih * 4 + i][j] = mfma16(af[i], bfr[j], acc[ih * 4 + i][j]);
;       }
;     }
;     __builtin_amdgcn_s_setprio(0);
;     __builtin_amdgcn_sched_barrier(0);
;     __syncthreads();
;   }
; __device__ __forceinline__ void phase_win(const Params& p, int part, u16* smem, volatile LAS unsigned* vb_) {
;     ...
; #pragma unroll
;     for (int i = 0; i < 8; ++i)
; #pragma unroll
;       for (int j = 0; j < 4; ++j)
; #pragma unroll
;         for (int r = 0; r < 4; ++r)
;           smem[(wm * 128 + i * 16 + (lane >> 4) * 4 + r) * 264 + wn * 64 + j * 16 + (lane & 15)] = f2bf(acc[i][j][r]);
;     __syncthreads();
	s_add_i32 s37, s37, 1
	s_add_u32 s20, s20, 64
	s_addc_u32 s21, s21, 0
	s_addk_i32 s11, 0x4000
	s_and_b32 s38, s11, 0x4000
	s_xor_b32 s39, s38, 0x4000
	s_lshl_b32 s39, s39, 1
	v_add_u32_e32 v228, s39, v185
	v_add_u32_e32 v229, s39, v186
	s_cmp_lt_u32 s37, 14
	s_cselect_b32 s49, s21, s13
	s_cselect_b32 s48, s20, s12
	s_cselect_b32 s51, s21, s47
	s_cselect_b32 s50, s20, s46
	s_lshl_b64 s[48:49], s[48:49], 1
	s_lshl_b64 s[50:51], s[50:51], 1
	s_add_u32 s52, s62, s48
	s_addc_u32 s53, s63, s49
	s_add_u32 s66, s64, s50
	s_addc_u32 s67, s65, s51
	s_lshl_b32 s38, s38, 1
	v_add_u32_e32 v0, s38, v187
	v_add_u32_e32 v191, s38, v188
	s_setprio 1
	ds_read_b128 v[166:169], v191
	ds_read_b128 v[162:165], v0
	ds_read_b128 v[170:173], v191 offset:2048
	ds_read_b128 v[192:195], v191 offset:4096
	ds_read_b128 v[196:199], v191 offset:6144
	v_mfma_f32_16x16x32_bf16 v[78:81], v[212:215], v[204:207], v[78:81]
	v_mfma_f32_16x16x32_bf16 v[74:77], v[216:219], v[204:207], v[74:77]
	v_mfma_f32_16x16x32_bf16 v[70:73], v[220:223], v[204:207], v[70:73]
	v_mfma_f32_16x16x32_bf16 v[66:69], v[224:227], v[204:207], v[66:69]
	ds_read_b128 v[204:207], v0 offset:2048
	v_mfma_f32_16x16x32_bf16 v[62:65], v[212:215], v[208:211], v[62:65]
	v_mfma_f32_16x16x32_bf16 v[58:61], v[216:219], v[208:211], v[58:61]
	v_mfma_f32_16x16x32_bf16 v[54:57], v[220:223], v[208:211], v[54:57]
	v_mfma_f32_16x16x32_bf16 v[50:53], v[224:227], v[208:211], v[50:53]
	ds_read_b128 v[208:211], v0 offset:4096
	v_mfma_f32_16x16x32_bf16 v[46:49], v[212:215], v[238:241], v[46:49]
	v_mfma_f32_16x16x32_bf16 v[42:45], v[216:219], v[238:241], v[42:45]
	v_mfma_f32_16x16x32_bf16 v[38:41], v[220:223], v[238:241], v[38:41]
	v_mfma_f32_16x16x32_bf16 v[34:37], v[224:227], v[238:241], v[34:37]
	ds_read_b128 v[238:241], v0 offset:6144
	v_add_u32_e32 v191, v191, v190
	s_setprio 0
	s_cmpk_lg_i32 s20, 0x480
	s_cbranch_scc1 .LBB0_470
	v_and_b32_e32 v228, 15, v175
	v_bfe_u32 v229, v175, 8, 1
	v_lshl_or_b32 v228, v229, 7, v228
	v_mul_u32_u24_e32 v228, 0x210, v228
	v_bfe_u32 v229, v175, 6, 2
	v_lshl_add_u32 v228, v229, 7, v228
	v_bfe_u32 v229, v175, 4, 2
	v_lshl_add_u32 v228, v229, 3, v228
	v_cvt_pk_bf16_f32 v158, v158, v159
	v_cvt_pk_bf16_f32 v159, v160, v161
	v_cvt_pk_bf16_f32 v154, v154, v155
	v_cvt_pk_bf16_f32 v155, v156, v157
	v_cvt_pk_bf16_f32 v150, v150, v151
	v_cvt_pk_bf16_f32 v151, v152, v153
	v_cvt_pk_bf16_f32 v146, v146, v147
	v_cvt_pk_bf16_f32 v147, v148, v149
	ds_write_b64 v228, v[158:159]
	ds_write_b64 v228, v[154:155] offset:32
	ds_write_b64 v228, v[150:151] offset:64
	ds_write_b64 v228, v[146:147] offset:96
	v_cvt_pk_bf16_f32 v142, v142, v143
	v_cvt_pk_bf16_f32 v143, v144, v145
	v_cvt_pk_bf16_f32 v138, v138, v139
	v_cvt_pk_bf16_f32 v139, v140, v141
	v_cvt_pk_bf16_f32 v134, v134, v135
	v_cvt_pk_bf16_f32 v135, v136, v137
	v_cvt_pk_bf16_f32 v130, v130, v131
	v_cvt_pk_bf16_f32 v131, v132, v133
	ds_write_b64 v228, v[142:143] offset:8448
	ds_write_b64 v228, v[138:139] offset:8480
	ds_write_b64 v228, v[134:135] offset:8512
	ds_write_b64 v228, v[130:131] offset:8544
	v_cvt_pk_bf16_f32 v126, v126, v127
	v_cvt_pk_bf16_f32 v127, v128, v129
	v_cvt_pk_bf16_f32 v122, v122, v123
	v_cvt_pk_bf16_f32 v123, v124, v125
	v_cvt_pk_bf16_f32 v118, v118, v119
	v_cvt_pk_bf16_f32 v119, v120, v121
	v_cvt_pk_bf16_f32 v114, v114, v115
	v_cvt_pk_bf16_f32 v115, v116, v117
	ds_write_b64 v228, v[126:127] offset:16896
	ds_write_b64 v228, v[122:123] offset:16928
	ds_write_b64 v228, v[118:119] offset:16960
	ds_write_b64 v228, v[114:115] offset:16992
	v_cvt_pk_bf16_f32 v110, v110, v111
	v_cvt_pk_bf16_f32 v111, v112, v113
	v_cvt_pk_bf16_f32 v106, v106, v107
	v_cvt_pk_bf16_f32 v107, v108, v109
	v_cvt_pk_bf16_f32 v102, v102, v103
	v_cvt_pk_bf16_f32 v103, v104, v105
	v_cvt_pk_bf16_f32 v98, v98, v99
	v_cvt_pk_bf16_f32 v99, v100, v101
	ds_write_b64 v228, v[110:111] offset:25344
	ds_write_b64 v228, v[106:107] offset:25376
	ds_write_b64 v228, v[102:103] offset:25408
	ds_write_b64 v228, v[98:99] offset:25440
	v_cvt_pk_bf16_f32 v94, v94, v95
	v_cvt_pk_bf16_f32 v95, v96, v97
	v_cvt_pk_bf16_f32 v90, v90, v91
	v_cvt_pk_bf16_f32 v91, v92, v93
	v_cvt_pk_bf16_f32 v86, v86, v87
	v_cvt_pk_bf16_f32 v87, v88, v89
	v_cvt_pk_bf16_f32 v82, v82, v83
	v_cvt_pk_bf16_f32 v83, v84, v85
	ds_write_b64 v228, v[94:95] offset:33792
	ds_write_b64 v228, v[90:91] offset:33824
	ds_write_b64 v228, v[86:87] offset:33856
	ds_write_b64 v228, v[82:83] offset:33888
	v_cvt_pk_bf16_f32 v78, v78, v79
	v_cvt_pk_bf16_f32 v79, v80, v81
	v_cvt_pk_bf16_f32 v74, v74, v75
	v_cvt_pk_bf16_f32 v75, v76, v77
	v_cvt_pk_bf16_f32 v70, v70, v71
	v_cvt_pk_bf16_f32 v71, v72, v73
	v_cvt_pk_bf16_f32 v66, v66, v67
	v_cvt_pk_bf16_f32 v67, v68, v69
	ds_write_b64 v228, v[78:79] offset:42240
	ds_write_b64 v228, v[74:75] offset:42272
	ds_write_b64 v228, v[70:71] offset:42304
	ds_write_b64 v228, v[66:67] offset:42336
	v_cvt_pk_bf16_f32 v62, v62, v63
	v_cvt_pk_bf16_f32 v63, v64, v65
	v_cvt_pk_bf16_f32 v58, v58, v59
	v_cvt_pk_bf16_f32 v59, v60, v61
	v_cvt_pk_bf16_f32 v54, v54, v55
	v_cvt_pk_bf16_f32 v55, v56, v57
	v_cvt_pk_bf16_f32 v50, v50, v51
	v_cvt_pk_bf16_f32 v51, v52, v53
	ds_write_b64 v228, v[62:63] offset:50688
	ds_write_b64 v228, v[58:59] offset:50720
	ds_write_b64 v228, v[54:55] offset:50752
	ds_write_b64 v228, v[50:51] offset:50784
	v_cvt_pk_bf16_f32 v46, v46, v47
	v_cvt_pk_bf16_f32 v47, v48, v49
	v_cvt_pk_bf16_f32 v42, v42, v43
	v_cvt_pk_bf16_f32 v43, v44, v45
	v_cvt_pk_bf16_f32 v38, v38, v39
	v_cvt_pk_bf16_f32 v39, v40, v41
	v_cvt_pk_bf16_f32 v34, v34, v35
	v_cvt_pk_bf16_f32 v35, v36, v37
	ds_write_b64 v228, v[46:47] offset:59136
	ds_write_b64 v228, v[42:43] offset:59168
	ds_write_b64 v228, v[38:39] offset:59200
	ds_write_b64 v228, v[34:35] offset:59232
	v_mov_b32_e32 v43, v175
	s_waitcnt lgkmcnt(0)
	s_barrier
; #define RTID opaque_tid()
; __device__ __forceinline__ void phase_win(const Params& p, int part, u16* smem, volatile LAS unsigned* vb_) {
;     ...
;     const int tid2 = RTID;
; #pragma unroll
;     for (int k = 0; k < 16; ++k) {
;       const int c = tid2 + 512 * k;
;       const int row = c >> 5, ch = c & 31;
;       const uint4 v = *(const uint4*)(smem + row * 264 + ch * 8);
;       u16* d_ = (ch < 16) ? dstA : dstB;
;       const int l_ = (ch < 16) ? ldA : ldB;
;       *(uint4*)(d_ + (size_t)(mt * 256 + row) * l_ + (ch & 15) * 8) = v;
;     }
;     __syncthreads();
	s_mov_b32 s38, s36
	v_and_b32_e32 v0, 31, v43
	v_lshlrev_b32_e32 v40, 4, v0
	v_mov_b32_e32 v41, 0
	v_ashrrev_i32_e32 v0, 5, v43
	v_mad_u32_u24 v34, v0, s2, v40
	v_add_u32_e32 v35, 0x10800, v34
	ds_read_b128 v[48:51], v34
	ds_read_b128 v[52:55], v34 offset:8448
	ds_read_b128 v[56:59], v34 offset:16896
	ds_read_b128 v[60:63], v34 offset:25344
	ds_read_b128 v[64:67], v34 offset:33792
	ds_read_b128 v[68:71], v34 offset:42240
	ds_read_b128 v[72:75], v34 offset:50688
	ds_read_b128 v[76:79], v34 offset:59136
	v_add_u32_e32 v0, s10, v0
	v_mad_u64_u32 v[38:39], s[12:13], v0, s0, 0
	v_lshl_add_u64 v[38:39], v[38:39], 1, v[40:41]
	v_lshl_add_u64 v[46:47], s[44:45], 0, v[38:39]
	s_lshl_b32 s48, s0, 5
	s_mov_b32 s49, 0
	s_and_b64 vcc, exec, s[42:43]
	s_waitcnt lgkmcnt(7)
	global_store_dwordx4 v[46:47], v[48:51], off
	s_nop 0
	ds_read_b128 v[48:51], v35
	v_lshl_add_u64 v[46:47], v[46:47], 0, s[48:49]
	s_waitcnt lgkmcnt(7)
	global_store_dwordx4 v[46:47], v[52:55], off
	s_nop 0
	ds_read_b128 v[52:55], v35 offset:8448
	v_lshl_add_u64 v[46:47], v[46:47], 0, s[48:49]
	s_waitcnt lgkmcnt(7)
	global_store_dwordx4 v[46:47], v[56:59], off
	s_nop 0
	ds_read_b128 v[56:59], v35 offset:16896
	v_lshl_add_u64 v[46:47], v[46:47], 0, s[48:49]
	s_waitcnt lgkmcnt(7)
	global_store_dwordx4 v[46:47], v[60:63], off
	s_nop 0
	ds_read_b128 v[60:63], v35 offset:25344
	v_lshl_add_u64 v[46:47], v[46:47], 0, s[48:49]
	s_waitcnt lgkmcnt(7)
	global_store_dwordx4 v[46:47], v[64:67], off
	s_nop 0
	ds_read_b128 v[64:67], v35 offset:33792
	v_lshl_add_u64 v[46:47], v[46:47], 0, s[48:49]
	s_waitcnt lgkmcnt(7)
	global_store_dwordx4 v[46:47], v[68:71], off
	s_nop 0
	ds_read_b128 v[68:71], v35 offset:42240
	v_lshl_add_u64 v[46:47], v[46:47], 0, s[48:49]
	s_waitcnt lgkmcnt(7)
	global_store_dwordx4 v[46:47], v[72:75], off
	s_nop 0
	ds_read_b128 v[72:75], v35 offset:50688
	v_lshl_add_u64 v[46:47], v[46:47], 0, s[48:49]
	s_waitcnt lgkmcnt(7)
	global_store_dwordx4 v[46:47], v[76:79], off
	s_nop 0
	ds_read_b128 v[76:79], v35 offset:59136
	v_lshl_add_u64 v[46:47], v[46:47], 0, s[48:49]
	s_waitcnt lgkmcnt(7)
	global_store_dwordx4 v[46:47], v[48:51], off
	v_lshl_add_u64 v[46:47], v[46:47], 0, s[48:49]
	s_waitcnt lgkmcnt(6)
	global_store_dwordx4 v[46:47], v[52:55], off
	v_lshl_add_u64 v[46:47], v[46:47], 0, s[48:49]
	s_waitcnt lgkmcnt(5)
	global_store_dwordx4 v[46:47], v[56:59], off
	v_lshl_add_u64 v[46:47], v[46:47], 0, s[48:49]
	s_waitcnt lgkmcnt(4)
	global_store_dwordx4 v[46:47], v[60:63], off
	v_lshl_add_u64 v[46:47], v[46:47], 0, s[48:49]
	s_waitcnt lgkmcnt(3)
	global_store_dwordx4 v[46:47], v[64:67], off
	v_lshl_add_u64 v[46:47], v[46:47], 0, s[48:49]
	s_waitcnt lgkmcnt(2)
	global_store_dwordx4 v[46:47], v[68:71], off
	v_lshl_add_u64 v[46:47], v[46:47], 0, s[48:49]
	s_waitcnt lgkmcnt(1)
	global_store_dwordx4 v[46:47], v[72:75], off
	v_lshl_add_u64 v[46:47], v[46:47], 0, s[48:49]
	s_waitcnt lgkmcnt(0)
	global_store_dwordx4 v[46:47], v[76:79], off
	s_mov_b64 s[12:13], -1
	s_barrier
	s_cbranch_vccz .LBB0_441
